# SwiGLU epilogue rewritten with packed f32 VALU (v_pk_mul/add), fresh simple schedule, on top of GEMM peel
# baseline (speedup 1.0000x reference)
.LBB0_187:
	v_lshl_or_b32 v142, s65, 7, v146
	v_lshl_add_u32 v150, s36, 8, v144
	v_ashrrev_i32_e32 v143, 31, v142
	v_mov_b64_e32 v[140:141], s[22:23]
	v_mad_i64_i32 v[152:153], s[44:45], v150, s64, v[140:141]
	v_lshlrev_b64 v[142:143], 1, v[142:143]
	v_lshl_add_u64 v[152:153], v[152:153], 0, v[142:143]
	v_mov_b32_e32 v232, 0xbfb8aa3b
	v_mov_b64_e32 v[238:239], 0x16000
	v_mov_b64_e32 v[240:241], 0x6e000
	v_pk_mul_f32 v[234:235], v[232:233], v[124:125] op_sel_hi:[0,1]
	v_pk_mul_f32 v[236:237], v[232:233], v[126:127] op_sel_hi:[0,1]
	v_exp_f32_e32 v234, v234
	v_exp_f32_e32 v235, v235
	v_exp_f32_e32 v236, v236
	v_exp_f32_e32 v237, v237
	v_pk_add_f32 v[234:235], v[234:235], 1.0 op_sel_hi:[1,0]
	v_pk_add_f32 v[236:237], v[236:237], 1.0 op_sel_hi:[1,0]
	v_rcp_f32_e32 v234, v234
	v_rcp_f32_e32 v235, v235
	v_rcp_f32_e32 v236, v236
	v_rcp_f32_e32 v237, v237
	v_pk_mul_f32 v[234:235], v[124:125], v[234:235]
	v_pk_mul_f32 v[236:237], v[126:127], v[236:237]
	v_pk_mul_f32 v[120:121], v[120:121], v[234:235]
	v_pk_mul_f32 v[122:123], v[122:123], v[236:237]
	v_cvt_pk_bf16_f32 v120, v120, v121
	v_cvt_pk_bf16_f32 v121, v122, v123
	global_store_dwordx2 v[152:153], v[120:121], off
	v_pk_mul_f32 v[234:235], v[232:233], v[116:117] op_sel_hi:[0,1]
	v_pk_mul_f32 v[236:237], v[232:233], v[118:119] op_sel_hi:[0,1]
	v_exp_f32_e32 v234, v234
	v_exp_f32_e32 v235, v235
	v_exp_f32_e32 v236, v236
	v_exp_f32_e32 v237, v237
	v_pk_add_f32 v[234:235], v[234:235], 1.0 op_sel_hi:[1,0]
	v_pk_add_f32 v[236:237], v[236:237], 1.0 op_sel_hi:[1,0]
	v_rcp_f32_e32 v234, v234
	v_rcp_f32_e32 v235, v235
	v_rcp_f32_e32 v236, v236
	v_rcp_f32_e32 v237, v237
	v_pk_mul_f32 v[234:235], v[116:117], v[234:235]
	v_pk_mul_f32 v[236:237], v[118:119], v[236:237]
	v_pk_mul_f32 v[112:113], v[112:113], v[234:235]
	v_pk_mul_f32 v[114:115], v[114:115], v[236:237]
	v_cvt_pk_bf16_f32 v112, v112, v113
	v_cvt_pk_bf16_f32 v113, v114, v115
	global_store_dwordx2 v[152:153], v[112:113], off offset:128
	v_lshl_add_u64 v[152:153], v[152:153], 0, v[238:239]
	v_pk_mul_f32 v[234:235], v[232:233], v[108:109] op_sel_hi:[0,1]
	v_pk_mul_f32 v[236:237], v[232:233], v[110:111] op_sel_hi:[0,1]
	v_exp_f32_e32 v234, v234
	v_exp_f32_e32 v235, v235
	v_exp_f32_e32 v236, v236
	v_exp_f32_e32 v237, v237
	v_pk_add_f32 v[234:235], v[234:235], 1.0 op_sel_hi:[1,0]
	v_pk_add_f32 v[236:237], v[236:237], 1.0 op_sel_hi:[1,0]
	v_rcp_f32_e32 v234, v234
	v_rcp_f32_e32 v235, v235
	v_rcp_f32_e32 v236, v236
	v_rcp_f32_e32 v237, v237
	v_pk_mul_f32 v[234:235], v[108:109], v[234:235]
	v_pk_mul_f32 v[236:237], v[110:111], v[236:237]
	v_pk_mul_f32 v[104:105], v[104:105], v[234:235]
	v_pk_mul_f32 v[106:107], v[106:107], v[236:237]
	v_cvt_pk_bf16_f32 v104, v104, v105
	v_cvt_pk_bf16_f32 v105, v106, v107
	global_store_dwordx2 v[152:153], v[104:105], off
	v_pk_mul_f32 v[234:235], v[232:233], v[100:101] op_sel_hi:[0,1]
	v_pk_mul_f32 v[236:237], v[232:233], v[102:103] op_sel_hi:[0,1]
	v_exp_f32_e32 v234, v234
	v_exp_f32_e32 v235, v235
	v_exp_f32_e32 v236, v236
	v_exp_f32_e32 v237, v237
	v_pk_add_f32 v[234:235], v[234:235], 1.0 op_sel_hi:[1,0]
	v_pk_add_f32 v[236:237], v[236:237], 1.0 op_sel_hi:[1,0]
	v_rcp_f32_e32 v234, v234
	v_rcp_f32_e32 v235, v235
	v_rcp_f32_e32 v236, v236
	v_rcp_f32_e32 v237, v237
	v_pk_mul_f32 v[234:235], v[100:101], v[234:235]
	v_pk_mul_f32 v[236:237], v[102:103], v[236:237]
	v_pk_mul_f32 v[96:97], v[96:97], v[234:235]
	v_pk_mul_f32 v[98:99], v[98:99], v[236:237]
	v_cvt_pk_bf16_f32 v96, v96, v97
	v_cvt_pk_bf16_f32 v97, v98, v99
	global_store_dwordx2 v[152:153], v[96:97], off offset:128
	v_lshl_add_u64 v[152:153], v[152:153], 0, v[238:239]
	v_pk_mul_f32 v[234:235], v[232:233], v[92:93] op_sel_hi:[0,1]
	v_pk_mul_f32 v[236:237], v[232:233], v[94:95] op_sel_hi:[0,1]
	v_exp_f32_e32 v234, v234
	v_exp_f32_e32 v235, v235
	v_exp_f32_e32 v236, v236
	v_exp_f32_e32 v237, v237
	v_pk_add_f32 v[234:235], v[234:235], 1.0 op_sel_hi:[1,0]
	v_pk_add_f32 v[236:237], v[236:237], 1.0 op_sel_hi:[1,0]
	v_rcp_f32_e32 v234, v234
	v_rcp_f32_e32 v235, v235
	v_rcp_f32_e32 v236, v236
	v_rcp_f32_e32 v237, v237
	v_pk_mul_f32 v[234:235], v[92:93], v[234:235]
	v_pk_mul_f32 v[236:237], v[94:95], v[236:237]
	v_pk_mul_f32 v[88:89], v[88:89], v[234:235]
	v_pk_mul_f32 v[90:91], v[90:91], v[236:237]
	v_cvt_pk_bf16_f32 v88, v88, v89
	v_cvt_pk_bf16_f32 v89, v90, v91
	global_store_dwordx2 v[152:153], v[88:89], off
	v_pk_mul_f32 v[234:235], v[232:233], v[84:85] op_sel_hi:[0,1]
	v_pk_mul_f32 v[236:237], v[232:233], v[86:87] op_sel_hi:[0,1]
	v_exp_f32_e32 v234, v234
	v_exp_f32_e32 v235, v235
	v_exp_f32_e32 v236, v236
	v_exp_f32_e32 v237, v237
	v_pk_add_f32 v[234:235], v[234:235], 1.0 op_sel_hi:[1,0]
	v_pk_add_f32 v[236:237], v[236:237], 1.0 op_sel_hi:[1,0]
	v_rcp_f32_e32 v234, v234
	v_rcp_f32_e32 v235, v235
	v_rcp_f32_e32 v236, v236
	v_rcp_f32_e32 v237, v237
	v_pk_mul_f32 v[234:235], v[84:85], v[234:235]
	v_pk_mul_f32 v[236:237], v[86:87], v[236:237]
	v_pk_mul_f32 v[80:81], v[80:81], v[234:235]
	v_pk_mul_f32 v[82:83], v[82:83], v[236:237]
	v_cvt_pk_bf16_f32 v80, v80, v81
	v_cvt_pk_bf16_f32 v81, v82, v83
	global_store_dwordx2 v[152:153], v[80:81], off offset:128
	v_lshl_add_u64 v[152:153], v[152:153], 0, v[238:239]
	v_pk_mul_f32 v[234:235], v[232:233], v[76:77] op_sel_hi:[0,1]
	v_pk_mul_f32 v[236:237], v[232:233], v[78:79] op_sel_hi:[0,1]
	v_exp_f32_e32 v234, v234
	v_exp_f32_e32 v235, v235
	v_exp_f32_e32 v236, v236
	v_exp_f32_e32 v237, v237
	v_pk_add_f32 v[234:235], v[234:235], 1.0 op_sel_hi:[1,0]
	v_pk_add_f32 v[236:237], v[236:237], 1.0 op_sel_hi:[1,0]
	v_rcp_f32_e32 v234, v234
	v_rcp_f32_e32 v235, v235
	v_rcp_f32_e32 v236, v236
	v_rcp_f32_e32 v237, v237
	v_pk_mul_f32 v[234:235], v[76:77], v[234:235]
	v_pk_mul_f32 v[236:237], v[78:79], v[236:237]
	v_pk_mul_f32 v[72:73], v[72:73], v[234:235]
	v_pk_mul_f32 v[74:75], v[74:75], v[236:237]
	v_cvt_pk_bf16_f32 v72, v72, v73
	v_cvt_pk_bf16_f32 v73, v74, v75
	global_store_dwordx2 v[152:153], v[72:73], off
	v_pk_mul_f32 v[234:235], v[232:233], v[68:69] op_sel_hi:[0,1]
	v_pk_mul_f32 v[236:237], v[232:233], v[70:71] op_sel_hi:[0,1]
	v_exp_f32_e32 v234, v234
	v_exp_f32_e32 v235, v235
	v_exp_f32_e32 v236, v236
	v_exp_f32_e32 v237, v237
	v_pk_add_f32 v[234:235], v[234:235], 1.0 op_sel_hi:[1,0]
	v_pk_add_f32 v[236:237], v[236:237], 1.0 op_sel_hi:[1,0]
	v_rcp_f32_e32 v234, v234
	v_rcp_f32_e32 v235, v235
	v_rcp_f32_e32 v236, v236
	v_rcp_f32_e32 v237, v237
	v_pk_mul_f32 v[234:235], v[68:69], v[234:235]
	v_pk_mul_f32 v[236:237], v[70:71], v[236:237]
	v_pk_mul_f32 v[64:65], v[64:65], v[234:235]
	v_pk_mul_f32 v[66:67], v[66:67], v[236:237]
	v_cvt_pk_bf16_f32 v64, v64, v65
	v_cvt_pk_bf16_f32 v65, v66, v67
	global_store_dwordx2 v[152:153], v[64:65], off offset:128
	v_lshl_add_u64 v[152:153], v[152:153], 0, v[240:241]
	v_pk_mul_f32 v[234:235], v[232:233], v[60:61] op_sel_hi:[0,1]
	v_pk_mul_f32 v[236:237], v[232:233], v[62:63] op_sel_hi:[0,1]
	v_exp_f32_e32 v234, v234
	v_exp_f32_e32 v235, v235
	v_exp_f32_e32 v236, v236
	v_exp_f32_e32 v237, v237
	v_pk_add_f32 v[234:235], v[234:235], 1.0 op_sel_hi:[1,0]
	v_pk_add_f32 v[236:237], v[236:237], 1.0 op_sel_hi:[1,0]
	v_rcp_f32_e32 v234, v234
	v_rcp_f32_e32 v235, v235
	v_rcp_f32_e32 v236, v236
	v_rcp_f32_e32 v237, v237
	v_pk_mul_f32 v[234:235], v[60:61], v[234:235]
	v_pk_mul_f32 v[236:237], v[62:63], v[236:237]
	v_pk_mul_f32 v[56:57], v[56:57], v[234:235]
	v_pk_mul_f32 v[58:59], v[58:59], v[236:237]
	v_cvt_pk_bf16_f32 v56, v56, v57
	v_cvt_pk_bf16_f32 v57, v58, v59
	global_store_dwordx2 v[152:153], v[56:57], off
	v_pk_mul_f32 v[234:235], v[232:233], v[52:53] op_sel_hi:[0,1]
	v_pk_mul_f32 v[236:237], v[232:233], v[54:55] op_sel_hi:[0,1]
	v_exp_f32_e32 v234, v234
	v_exp_f32_e32 v235, v235
	v_exp_f32_e32 v236, v236
	v_exp_f32_e32 v237, v237
	v_pk_add_f32 v[234:235], v[234:235], 1.0 op_sel_hi:[1,0]
	v_pk_add_f32 v[236:237], v[236:237], 1.0 op_sel_hi:[1,0]
	v_rcp_f32_e32 v234, v234
	v_rcp_f32_e32 v235, v235
	v_rcp_f32_e32 v236, v236
	v_rcp_f32_e32 v237, v237
	v_pk_mul_f32 v[234:235], v[52:53], v[234:235]
	v_pk_mul_f32 v[236:237], v[54:55], v[236:237]
	v_pk_mul_f32 v[48:49], v[48:49], v[234:235]
	v_pk_mul_f32 v[50:51], v[50:51], v[236:237]
	v_cvt_pk_bf16_f32 v48, v48, v49
	v_cvt_pk_bf16_f32 v49, v50, v51
	global_store_dwordx2 v[152:153], v[48:49], off offset:128
	v_lshl_add_u64 v[152:153], v[152:153], 0, v[238:239]
	v_pk_mul_f32 v[234:235], v[232:233], v[44:45] op_sel_hi:[0,1]
	v_pk_mul_f32 v[236:237], v[232:233], v[46:47] op_sel_hi:[0,1]
	v_exp_f32_e32 v234, v234
	v_exp_f32_e32 v235, v235
	v_exp_f32_e32 v236, v236
	v_exp_f32_e32 v237, v237
	v_pk_add_f32 v[234:235], v[234:235], 1.0 op_sel_hi:[1,0]
	v_pk_add_f32 v[236:237], v[236:237], 1.0 op_sel_hi:[1,0]
	v_rcp_f32_e32 v234, v234
	v_rcp_f32_e32 v235, v235
	v_rcp_f32_e32 v236, v236
	v_rcp_f32_e32 v237, v237
	v_pk_mul_f32 v[234:235], v[44:45], v[234:235]
	v_pk_mul_f32 v[236:237], v[46:47], v[236:237]
	v_pk_mul_f32 v[40:41], v[40:41], v[234:235]
	v_pk_mul_f32 v[42:43], v[42:43], v[236:237]
	v_cvt_pk_bf16_f32 v40, v40, v41
	v_cvt_pk_bf16_f32 v41, v42, v43
	global_store_dwordx2 v[152:153], v[40:41], off
	v_pk_mul_f32 v[234:235], v[232:233], v[36:37] op_sel_hi:[0,1]
	v_pk_mul_f32 v[236:237], v[232:233], v[38:39] op_sel_hi:[0,1]
	v_exp_f32_e32 v234, v234
	v_exp_f32_e32 v235, v235
	v_exp_f32_e32 v236, v236
	v_exp_f32_e32 v237, v237
	v_pk_add_f32 v[234:235], v[234:235], 1.0 op_sel_hi:[1,0]
	v_pk_add_f32 v[236:237], v[236:237], 1.0 op_sel_hi:[1,0]
	v_rcp_f32_e32 v234, v234
	v_rcp_f32_e32 v235, v235
	v_rcp_f32_e32 v236, v236
	v_rcp_f32_e32 v237, v237
	v_pk_mul_f32 v[234:235], v[36:37], v[234:235]
	v_pk_mul_f32 v[236:237], v[38:39], v[236:237]
	v_pk_mul_f32 v[32:33], v[32:33], v[234:235]
	v_pk_mul_f32 v[34:35], v[34:35], v[236:237]
	v_cvt_pk_bf16_f32 v32, v32, v33
	v_cvt_pk_bf16_f32 v33, v34, v35
	global_store_dwordx2 v[152:153], v[32:33], off offset:128
	v_lshl_add_u64 v[152:153], v[152:153], 0, v[238:239]
	v_pk_mul_f32 v[234:235], v[232:233], v[28:29] op_sel_hi:[0,1]
	v_pk_mul_f32 v[236:237], v[232:233], v[30:31] op_sel_hi:[0,1]
	v_exp_f32_e32 v234, v234
	v_exp_f32_e32 v235, v235
	v_exp_f32_e32 v236, v236
	v_exp_f32_e32 v237, v237
	v_pk_add_f32 v[234:235], v[234:235], 1.0 op_sel_hi:[1,0]
	v_pk_add_f32 v[236:237], v[236:237], 1.0 op_sel_hi:[1,0]
	v_rcp_f32_e32 v234, v234
	v_rcp_f32_e32 v235, v235
	v_rcp_f32_e32 v236, v236
	v_rcp_f32_e32 v237, v237
	v_pk_mul_f32 v[234:235], v[28:29], v[234:235]
	v_pk_mul_f32 v[236:237], v[30:31], v[236:237]
	v_pk_mul_f32 v[24:25], v[24:25], v[234:235]
	v_pk_mul_f32 v[26:27], v[26:27], v[236:237]
	v_cvt_pk_bf16_f32 v24, v24, v25
	v_cvt_pk_bf16_f32 v25, v26, v27
	global_store_dwordx2 v[152:153], v[24:25], off
	v_pk_mul_f32 v[234:235], v[232:233], v[20:21] op_sel_hi:[0,1]
	v_pk_mul_f32 v[236:237], v[232:233], v[22:23] op_sel_hi:[0,1]
	v_exp_f32_e32 v234, v234
	v_exp_f32_e32 v235, v235
	v_exp_f32_e32 v236, v236
	v_exp_f32_e32 v237, v237
	v_pk_add_f32 v[234:235], v[234:235], 1.0 op_sel_hi:[1,0]
	v_pk_add_f32 v[236:237], v[236:237], 1.0 op_sel_hi:[1,0]
	v_rcp_f32_e32 v234, v234
	v_rcp_f32_e32 v235, v235
	v_rcp_f32_e32 v236, v236
	v_rcp_f32_e32 v237, v237
	v_pk_mul_f32 v[234:235], v[20:21], v[234:235]
	v_pk_mul_f32 v[236:237], v[22:23], v[236:237]
	v_pk_mul_f32 v[16:17], v[16:17], v[234:235]
	v_pk_mul_f32 v[18:19], v[18:19], v[236:237]
	v_cvt_pk_bf16_f32 v16, v16, v17
	v_cvt_pk_bf16_f32 v17, v18, v19
	global_store_dwordx2 v[152:153], v[16:17], off offset:128
	v_lshl_add_u64 v[152:153], v[152:153], 0, v[238:239]
	v_pk_mul_f32 v[234:235], v[232:233], v[12:13] op_sel_hi:[0,1]
	v_pk_mul_f32 v[236:237], v[232:233], v[14:15] op_sel_hi:[0,1]
	v_exp_f32_e32 v234, v234
	v_exp_f32_e32 v235, v235
	v_exp_f32_e32 v236, v236
	v_exp_f32_e32 v237, v237
	v_pk_add_f32 v[234:235], v[234:235], 1.0 op_sel_hi:[1,0]
	v_pk_add_f32 v[236:237], v[236:237], 1.0 op_sel_hi:[1,0]
	v_rcp_f32_e32 v234, v234
	v_rcp_f32_e32 v235, v235
	v_rcp_f32_e32 v236, v236
	v_rcp_f32_e32 v237, v237
	v_pk_mul_f32 v[234:235], v[12:13], v[234:235]
	v_pk_mul_f32 v[236:237], v[14:15], v[236:237]
	v_pk_mul_f32 v[8:9], v[8:9], v[234:235]
	v_pk_mul_f32 v[10:11], v[10:11], v[236:237]
	v_cvt_pk_bf16_f32 v8, v8, v9
	v_cvt_pk_bf16_f32 v9, v10, v11
	global_store_dwordx2 v[152:153], v[8:9], off
	v_pk_mul_f32 v[234:235], v[232:233], v[4:5] op_sel_hi:[0,1]
	v_pk_mul_f32 v[236:237], v[232:233], v[6:7] op_sel_hi:[0,1]
	v_exp_f32_e32 v234, v234
	v_exp_f32_e32 v235, v235
	v_exp_f32_e32 v236, v236
	v_exp_f32_e32 v237, v237
	v_pk_add_f32 v[234:235], v[234:235], 1.0 op_sel_hi:[1,0]
	v_pk_add_f32 v[236:237], v[236:237], 1.0 op_sel_hi:[1,0]
	v_rcp_f32_e32 v234, v234
	v_rcp_f32_e32 v235, v235
	v_rcp_f32_e32 v236, v236
	v_rcp_f32_e32 v237, v237
	v_pk_mul_f32 v[234:235], v[4:5], v[234:235]
	v_pk_mul_f32 v[236:237], v[6:7], v[236:237]
	v_pk_mul_f32 v[0:1], v[0:1], v[234:235]
	v_pk_mul_f32 v[2:3], v[2:3], v[236:237]
	v_cvt_pk_bf16_f32 v0, v0, v1
	v_cvt_pk_bf16_f32 v1, v2, v3
	global_store_dwordx2 v[152:153], v[0:1], off offset:128
	s_andn2_b64 vcc, exec, s[4:5]
	s_mov_b64 s[4:5], -1
	s_cbranch_vccnz .LBB0_180
	s_andn2_b64 vcc, exec, s[0:1]
	s_cbranch_vccnz .LBB0_179
	s_barrier
	s_branch .LBB0_179

.LBB0_727:
	v_lshl_or_b32 v142, s69, 7, v146
	v_lshl_add_u32 v150, s46, 8, v144
	v_ashrrev_i32_e32 v143, 31, v142
	v_mov_b64_e32 v[140:141], s[22:23]
	v_mad_i64_i32 v[152:153], s[48:49], v150, s68, v[140:141]
	v_lshlrev_b64 v[142:143], 1, v[142:143]
	v_lshl_add_u64 v[152:153], v[152:153], 0, v[142:143]
	v_mov_b32_e32 v232, 0xbfb8aa3b
	v_mov_b64_e32 v[238:239], 0x16000
	v_mov_b64_e32 v[240:241], 0x6e000
	v_pk_mul_f32 v[234:235], v[232:233], v[124:125] op_sel_hi:[0,1]
	v_pk_mul_f32 v[236:237], v[232:233], v[126:127] op_sel_hi:[0,1]
	v_exp_f32_e32 v234, v234
	v_exp_f32_e32 v235, v235
	v_exp_f32_e32 v236, v236
	v_exp_f32_e32 v237, v237
	v_pk_add_f32 v[234:235], v[234:235], 1.0 op_sel_hi:[1,0]
	v_pk_add_f32 v[236:237], v[236:237], 1.0 op_sel_hi:[1,0]
	v_rcp_f32_e32 v234, v234
	v_rcp_f32_e32 v235, v235
	v_rcp_f32_e32 v236, v236
	v_rcp_f32_e32 v237, v237
	v_pk_mul_f32 v[234:235], v[124:125], v[234:235]
	v_pk_mul_f32 v[236:237], v[126:127], v[236:237]
	v_pk_mul_f32 v[120:121], v[120:121], v[234:235]
	v_pk_mul_f32 v[122:123], v[122:123], v[236:237]
	v_cvt_pk_bf16_f32 v120, v120, v121
	v_cvt_pk_bf16_f32 v121, v122, v123
	global_store_dwordx2 v[152:153], v[120:121], off
	v_pk_mul_f32 v[234:235], v[232:233], v[116:117] op_sel_hi:[0,1]
	v_pk_mul_f32 v[236:237], v[232:233], v[118:119] op_sel_hi:[0,1]
	v_exp_f32_e32 v234, v234
	v_exp_f32_e32 v235, v235
	v_exp_f32_e32 v236, v236
	v_exp_f32_e32 v237, v237
	v_pk_add_f32 v[234:235], v[234:235], 1.0 op_sel_hi:[1,0]
	v_pk_add_f32 v[236:237], v[236:237], 1.0 op_sel_hi:[1,0]
	v_rcp_f32_e32 v234, v234
	v_rcp_f32_e32 v235, v235
	v_rcp_f32_e32 v236, v236
	v_rcp_f32_e32 v237, v237
	v_pk_mul_f32 v[234:235], v[116:117], v[234:235]
	v_pk_mul_f32 v[236:237], v[118:119], v[236:237]
	v_pk_mul_f32 v[112:113], v[112:113], v[234:235]
	v_pk_mul_f32 v[114:115], v[114:115], v[236:237]
	v_cvt_pk_bf16_f32 v112, v112, v113
	v_cvt_pk_bf16_f32 v113, v114, v115
	global_store_dwordx2 v[152:153], v[112:113], off offset:128
	v_lshl_add_u64 v[152:153], v[152:153], 0, v[238:239]
	v_pk_mul_f32 v[234:235], v[232:233], v[108:109] op_sel_hi:[0,1]
	v_pk_mul_f32 v[236:237], v[232:233], v[110:111] op_sel_hi:[0,1]
	v_exp_f32_e32 v234, v234
	v_exp_f32_e32 v235, v235
	v_exp_f32_e32 v236, v236
	v_exp_f32_e32 v237, v237
	v_pk_add_f32 v[234:235], v[234:235], 1.0 op_sel_hi:[1,0]
	v_pk_add_f32 v[236:237], v[236:237], 1.0 op_sel_hi:[1,0]
	v_rcp_f32_e32 v234, v234
	v_rcp_f32_e32 v235, v235
	v_rcp_f32_e32 v236, v236
	v_rcp_f32_e32 v237, v237
	v_pk_mul_f32 v[234:235], v[108:109], v[234:235]
	v_pk_mul_f32 v[236:237], v[110:111], v[236:237]
	v_pk_mul_f32 v[104:105], v[104:105], v[234:235]
	v_pk_mul_f32 v[106:107], v[106:107], v[236:237]
	v_cvt_pk_bf16_f32 v104, v104, v105
	v_cvt_pk_bf16_f32 v105, v106, v107
	global_store_dwordx2 v[152:153], v[104:105], off
	v_pk_mul_f32 v[234:235], v[232:233], v[100:101] op_sel_hi:[0,1]
	v_pk_mul_f32 v[236:237], v[232:233], v[102:103] op_sel_hi:[0,1]
	v_exp_f32_e32 v234, v234
	v_exp_f32_e32 v235, v235
	v_exp_f32_e32 v236, v236
	v_exp_f32_e32 v237, v237
	v_pk_add_f32 v[234:235], v[234:235], 1.0 op_sel_hi:[1,0]
	v_pk_add_f32 v[236:237], v[236:237], 1.0 op_sel_hi:[1,0]
	v_rcp_f32_e32 v234, v234
	v_rcp_f32_e32 v235, v235
	v_rcp_f32_e32 v236, v236
	v_rcp_f32_e32 v237, v237
	v_pk_mul_f32 v[234:235], v[100:101], v[234:235]
	v_pk_mul_f32 v[236:237], v[102:103], v[236:237]
	v_pk_mul_f32 v[96:97], v[96:97], v[234:235]
	v_pk_mul_f32 v[98:99], v[98:99], v[236:237]
	v_cvt_pk_bf16_f32 v96, v96, v97
	v_cvt_pk_bf16_f32 v97, v98, v99
	global_store_dwordx2 v[152:153], v[96:97], off offset:128
	v_lshl_add_u64 v[152:153], v[152:153], 0, v[238:239]
	v_pk_mul_f32 v[234:235], v[232:233], v[92:93] op_sel_hi:[0,1]
	v_pk_mul_f32 v[236:237], v[232:233], v[94:95] op_sel_hi:[0,1]
	v_exp_f32_e32 v234, v234
	v_exp_f32_e32 v235, v235
	v_exp_f32_e32 v236, v236
	v_exp_f32_e32 v237, v237
	v_pk_add_f32 v[234:235], v[234:235], 1.0 op_sel_hi:[1,0]
	v_pk_add_f32 v[236:237], v[236:237], 1.0 op_sel_hi:[1,0]
	v_rcp_f32_e32 v234, v234
	v_rcp_f32_e32 v235, v235
	v_rcp_f32_e32 v236, v236
	v_rcp_f32_e32 v237, v237
	v_pk_mul_f32 v[234:235], v[92:93], v[234:235]
	v_pk_mul_f32 v[236:237], v[94:95], v[236:237]
	v_pk_mul_f32 v[88:89], v[88:89], v[234:235]
	v_pk_mul_f32 v[90:91], v[90:91], v[236:237]
	v_cvt_pk_bf16_f32 v88, v88, v89
	v_cvt_pk_bf16_f32 v89, v90, v91
	global_store_dwordx2 v[152:153], v[88:89], off
	v_pk_mul_f32 v[234:235], v[232:233], v[84:85] op_sel_hi:[0,1]
	v_pk_mul_f32 v[236:237], v[232:233], v[86:87] op_sel_hi:[0,1]
	v_exp_f32_e32 v234, v234
	v_exp_f32_e32 v235, v235
	v_exp_f32_e32 v236, v236
	v_exp_f32_e32 v237, v237
	v_pk_add_f32 v[234:235], v[234:235], 1.0 op_sel_hi:[1,0]
	v_pk_add_f32 v[236:237], v[236:237], 1.0 op_sel_hi:[1,0]
	v_rcp_f32_e32 v234, v234
	v_rcp_f32_e32 v235, v235
	v_rcp_f32_e32 v236, v236
	v_rcp_f32_e32 v237, v237
	v_pk_mul_f32 v[234:235], v[84:85], v[234:235]
	v_pk_mul_f32 v[236:237], v[86:87], v[236:237]
	v_pk_mul_f32 v[80:81], v[80:81], v[234:235]
	v_pk_mul_f32 v[82:83], v[82:83], v[236:237]
	v_cvt_pk_bf16_f32 v80, v80, v81
	v_cvt_pk_bf16_f32 v81, v82, v83
	global_store_dwordx2 v[152:153], v[80:81], off offset:128
	v_lshl_add_u64 v[152:153], v[152:153], 0, v[238:239]
	v_pk_mul_f32 v[234:235], v[232:233], v[76:77] op_sel_hi:[0,1]
	v_pk_mul_f32 v[236:237], v[232:233], v[78:79] op_sel_hi:[0,1]
	v_exp_f32_e32 v234, v234
	v_exp_f32_e32 v235, v235
	v_exp_f32_e32 v236, v236
	v_exp_f32_e32 v237, v237
	v_pk_add_f32 v[234:235], v[234:235], 1.0 op_sel_hi:[1,0]
	v_pk_add_f32 v[236:237], v[236:237], 1.0 op_sel_hi:[1,0]
	v_rcp_f32_e32 v234, v234
	v_rcp_f32_e32 v235, v235
	v_rcp_f32_e32 v236, v236
	v_rcp_f32_e32 v237, v237
	v_pk_mul_f32 v[234:235], v[76:77], v[234:235]
	v_pk_mul_f32 v[236:237], v[78:79], v[236:237]
	v_pk_mul_f32 v[72:73], v[72:73], v[234:235]
	v_pk_mul_f32 v[74:75], v[74:75], v[236:237]
	v_cvt_pk_bf16_f32 v72, v72, v73
	v_cvt_pk_bf16_f32 v73, v74, v75
	global_store_dwordx2 v[152:153], v[72:73], off
	v_pk_mul_f32 v[234:235], v[232:233], v[68:69] op_sel_hi:[0,1]
	v_pk_mul_f32 v[236:237], v[232:233], v[70:71] op_sel_hi:[0,1]
	v_exp_f32_e32 v234, v234
	v_exp_f32_e32 v235, v235
	v_exp_f32_e32 v236, v236
	v_exp_f32_e32 v237, v237
	v_pk_add_f32 v[234:235], v[234:235], 1.0 op_sel_hi:[1,0]
	v_pk_add_f32 v[236:237], v[236:237], 1.0 op_sel_hi:[1,0]
	v_rcp_f32_e32 v234, v234
	v_rcp_f32_e32 v235, v235
	v_rcp_f32_e32 v236, v236
	v_rcp_f32_e32 v237, v237
	v_pk_mul_f32 v[234:235], v[68:69], v[234:235]
	v_pk_mul_f32 v[236:237], v[70:71], v[236:237]
	v_pk_mul_f32 v[64:65], v[64:65], v[234:235]
	v_pk_mul_f32 v[66:67], v[66:67], v[236:237]
	v_cvt_pk_bf16_f32 v64, v64, v65
	v_cvt_pk_bf16_f32 v65, v66, v67
	global_store_dwordx2 v[152:153], v[64:65], off offset:128
	v_lshl_add_u64 v[152:153], v[152:153], 0, v[240:241]
	v_pk_mul_f32 v[234:235], v[232:233], v[60:61] op_sel_hi:[0,1]
	v_pk_mul_f32 v[236:237], v[232:233], v[62:63] op_sel_hi:[0,1]
	v_exp_f32_e32 v234, v234
	v_exp_f32_e32 v235, v235
	v_exp_f32_e32 v236, v236
	v_exp_f32_e32 v237, v237
	v_pk_add_f32 v[234:235], v[234:235], 1.0 op_sel_hi:[1,0]
	v_pk_add_f32 v[236:237], v[236:237], 1.0 op_sel_hi:[1,0]
	v_rcp_f32_e32 v234, v234
	v_rcp_f32_e32 v235, v235
	v_rcp_f32_e32 v236, v236
	v_rcp_f32_e32 v237, v237
	v_pk_mul_f32 v[234:235], v[60:61], v[234:235]
	v_pk_mul_f32 v[236:237], v[62:63], v[236:237]
	v_pk_mul_f32 v[56:57], v[56:57], v[234:235]
	v_pk_mul_f32 v[58:59], v[58:59], v[236:237]
	v_cvt_pk_bf16_f32 v56, v56, v57
	v_cvt_pk_bf16_f32 v57, v58, v59
	global_store_dwordx2 v[152:153], v[56:57], off
	v_pk_mul_f32 v[234:235], v[232:233], v[52:53] op_sel_hi:[0,1]
	v_pk_mul_f32 v[236:237], v[232:233], v[54:55] op_sel_hi:[0,1]
	v_exp_f32_e32 v234, v234
	v_exp_f32_e32 v235, v235
	v_exp_f32_e32 v236, v236
	v_exp_f32_e32 v237, v237
	v_pk_add_f32 v[234:235], v[234:235], 1.0 op_sel_hi:[1,0]
	v_pk_add_f32 v[236:237], v[236:237], 1.0 op_sel_hi:[1,0]
	v_rcp_f32_e32 v234, v234
	v_rcp_f32_e32 v235, v235
	v_rcp_f32_e32 v236, v236
	v_rcp_f32_e32 v237, v237
	v_pk_mul_f32 v[234:235], v[52:53], v[234:235]
	v_pk_mul_f32 v[236:237], v[54:55], v[236:237]
	v_pk_mul_f32 v[48:49], v[48:49], v[234:235]
	v_pk_mul_f32 v[50:51], v[50:51], v[236:237]
	v_cvt_pk_bf16_f32 v48, v48, v49
	v_cvt_pk_bf16_f32 v49, v50, v51
	global_store_dwordx2 v[152:153], v[48:49], off offset:128
	v_lshl_add_u64 v[152:153], v[152:153], 0, v[238:239]
	v_pk_mul_f32 v[234:235], v[232:233], v[44:45] op_sel_hi:[0,1]
	v_pk_mul_f32 v[236:237], v[232:233], v[46:47] op_sel_hi:[0,1]
	v_exp_f32_e32 v234, v234
	v_exp_f32_e32 v235, v235
	v_exp_f32_e32 v236, v236
	v_exp_f32_e32 v237, v237
	v_pk_add_f32 v[234:235], v[234:235], 1.0 op_sel_hi:[1,0]
	v_pk_add_f32 v[236:237], v[236:237], 1.0 op_sel_hi:[1,0]
	v_rcp_f32_e32 v234, v234
	v_rcp_f32_e32 v235, v235
	v_rcp_f32_e32 v236, v236
	v_rcp_f32_e32 v237, v237
	v_pk_mul_f32 v[234:235], v[44:45], v[234:235]
	v_pk_mul_f32 v[236:237], v[46:47], v[236:237]
	v_pk_mul_f32 v[40:41], v[40:41], v[234:235]
	v_pk_mul_f32 v[42:43], v[42:43], v[236:237]
	v_cvt_pk_bf16_f32 v40, v40, v41
	v_cvt_pk_bf16_f32 v41, v42, v43
	global_store_dwordx2 v[152:153], v[40:41], off
	v_pk_mul_f32 v[234:235], v[232:233], v[36:37] op_sel_hi:[0,1]
	v_pk_mul_f32 v[236:237], v[232:233], v[38:39] op_sel_hi:[0,1]
	v_exp_f32_e32 v234, v234
	v_exp_f32_e32 v235, v235
	v_exp_f32_e32 v236, v236
	v_exp_f32_e32 v237, v237
	v_pk_add_f32 v[234:235], v[234:235], 1.0 op_sel_hi:[1,0]
	v_pk_add_f32 v[236:237], v[236:237], 1.0 op_sel_hi:[1,0]
	v_rcp_f32_e32 v234, v234
	v_rcp_f32_e32 v235, v235
	v_rcp_f32_e32 v236, v236
	v_rcp_f32_e32 v237, v237
	v_pk_mul_f32 v[234:235], v[36:37], v[234:235]
	v_pk_mul_f32 v[236:237], v[38:39], v[236:237]
	v_pk_mul_f32 v[32:33], v[32:33], v[234:235]
	v_pk_mul_f32 v[34:35], v[34:35], v[236:237]
	v_cvt_pk_bf16_f32 v32, v32, v33
	v_cvt_pk_bf16_f32 v33, v34, v35
	global_store_dwordx2 v[152:153], v[32:33], off offset:128
	v_lshl_add_u64 v[152:153], v[152:153], 0, v[238:239]
	v_pk_mul_f32 v[234:235], v[232:233], v[28:29] op_sel_hi:[0,1]
	v_pk_mul_f32 v[236:237], v[232:233], v[30:31] op_sel_hi:[0,1]
	v_exp_f32_e32 v234, v234
	v_exp_f32_e32 v235, v235
	v_exp_f32_e32 v236, v236
	v_exp_f32_e32 v237, v237
	v_pk_add_f32 v[234:235], v[234:235], 1.0 op_sel_hi:[1,0]
	v_pk_add_f32 v[236:237], v[236:237], 1.0 op_sel_hi:[1,0]
	v_rcp_f32_e32 v234, v234
	v_rcp_f32_e32 v235, v235
	v_rcp_f32_e32 v236, v236
	v_rcp_f32_e32 v237, v237
	v_pk_mul_f32 v[234:235], v[28:29], v[234:235]
	v_pk_mul_f32 v[236:237], v[30:31], v[236:237]
	v_pk_mul_f32 v[24:25], v[24:25], v[234:235]
	v_pk_mul_f32 v[26:27], v[26:27], v[236:237]
	v_cvt_pk_bf16_f32 v24, v24, v25
	v_cvt_pk_bf16_f32 v25, v26, v27
	global_store_dwordx2 v[152:153], v[24:25], off
	v_pk_mul_f32 v[234:235], v[232:233], v[20:21] op_sel_hi:[0,1]
	v_pk_mul_f32 v[236:237], v[232:233], v[22:23] op_sel_hi:[0,1]
	v_exp_f32_e32 v234, v234
	v_exp_f32_e32 v235, v235
	v_exp_f32_e32 v236, v236
	v_exp_f32_e32 v237, v237
	v_pk_add_f32 v[234:235], v[234:235], 1.0 op_sel_hi:[1,0]
	v_pk_add_f32 v[236:237], v[236:237], 1.0 op_sel_hi:[1,0]
	v_rcp_f32_e32 v234, v234
	v_rcp_f32_e32 v235, v235
	v_rcp_f32_e32 v236, v236
	v_rcp_f32_e32 v237, v237
	v_pk_mul_f32 v[234:235], v[20:21], v[234:235]
	v_pk_mul_f32 v[236:237], v[22:23], v[236:237]
	v_pk_mul_f32 v[16:17], v[16:17], v[234:235]
	v_pk_mul_f32 v[18:19], v[18:19], v[236:237]
	v_cvt_pk_bf16_f32 v16, v16, v17
	v_cvt_pk_bf16_f32 v17, v18, v19
	global_store_dwordx2 v[152:153], v[16:17], off offset:128
	v_lshl_add_u64 v[152:153], v[152:153], 0, v[238:239]
	v_pk_mul_f32 v[234:235], v[232:233], v[12:13] op_sel_hi:[0,1]
	v_pk_mul_f32 v[236:237], v[232:233], v[14:15] op_sel_hi:[0,1]
	v_exp_f32_e32 v234, v234
	v_exp_f32_e32 v235, v235
	v_exp_f32_e32 v236, v236
	v_exp_f32_e32 v237, v237
	v_pk_add_f32 v[234:235], v[234:235], 1.0 op_sel_hi:[1,0]
	v_pk_add_f32 v[236:237], v[236:237], 1.0 op_sel_hi:[1,0]
	v_rcp_f32_e32 v234, v234
	v_rcp_f32_e32 v235, v235
	v_rcp_f32_e32 v236, v236
	v_rcp_f32_e32 v237, v237
	v_pk_mul_f32 v[234:235], v[12:13], v[234:235]
	v_pk_mul_f32 v[236:237], v[14:15], v[236:237]
	v_pk_mul_f32 v[8:9], v[8:9], v[234:235]
	v_pk_mul_f32 v[10:11], v[10:11], v[236:237]
	v_cvt_pk_bf16_f32 v8, v8, v9
	v_cvt_pk_bf16_f32 v9, v10, v11
	global_store_dwordx2 v[152:153], v[8:9], off
	v_pk_mul_f32 v[234:235], v[232:233], v[4:5] op_sel_hi:[0,1]
	v_pk_mul_f32 v[236:237], v[232:233], v[6:7] op_sel_hi:[0,1]
	v_exp_f32_e32 v234, v234
	v_exp_f32_e32 v235, v235
	v_exp_f32_e32 v236, v236
	v_exp_f32_e32 v237, v237
	v_pk_add_f32 v[234:235], v[234:235], 1.0 op_sel_hi:[1,0]
	v_pk_add_f32 v[236:237], v[236:237], 1.0 op_sel_hi:[1,0]
	v_rcp_f32_e32 v234, v234
	v_rcp_f32_e32 v235, v235
	v_rcp_f32_e32 v236, v236
	v_rcp_f32_e32 v237, v237
	v_pk_mul_f32 v[234:235], v[4:5], v[234:235]
	v_pk_mul_f32 v[236:237], v[6:7], v[236:237]
	v_pk_mul_f32 v[0:1], v[0:1], v[234:235]
	v_pk_mul_f32 v[2:3], v[2:3], v[236:237]
	v_cvt_pk_bf16_f32 v0, v0, v1
	v_cvt_pk_bf16_f32 v1, v2, v3
	global_store_dwordx2 v[152:153], v[0:1], off offset:128
	s_andn2_b64 vcc, exec, s[10:11]
	s_mov_b64 s[10:11], -1
	s_cbranch_vccnz .LBB0_720
	s_andn2_b64 vcc, exec, s[0:1]
	s_cbranch_vccnz .LBB0_719
	s_barrier
	s_branch .LBB0_719

.LBB0_954:
	v_lshl_or_b32 v142, s71, 7, v146
	v_lshl_add_u32 v150, s48, 8, v144
	v_ashrrev_i32_e32 v143, 31, v142
	v_mov_b64_e32 v[140:141], s[22:23]
	v_mad_i64_i32 v[152:153], s[52:53], v150, s70, v[140:141]
	v_lshlrev_b64 v[142:143], 1, v[142:143]
	v_lshl_add_u64 v[152:153], v[152:153], 0, v[142:143]
	v_mov_b32_e32 v232, 0xbfb8aa3b
	v_mov_b64_e32 v[238:239], 0x16000
	v_mov_b64_e32 v[240:241], 0x6e000
	v_pk_mul_f32 v[234:235], v[232:233], v[124:125] op_sel_hi:[0,1]
	v_pk_mul_f32 v[236:237], v[232:233], v[126:127] op_sel_hi:[0,1]
	v_exp_f32_e32 v234, v234
	v_exp_f32_e32 v235, v235
	v_exp_f32_e32 v236, v236
	v_exp_f32_e32 v237, v237
	v_pk_add_f32 v[234:235], v[234:235], 1.0 op_sel_hi:[1,0]
	v_pk_add_f32 v[236:237], v[236:237], 1.0 op_sel_hi:[1,0]
	v_rcp_f32_e32 v234, v234
	v_rcp_f32_e32 v235, v235
	v_rcp_f32_e32 v236, v236
	v_rcp_f32_e32 v237, v237
	v_pk_mul_f32 v[234:235], v[124:125], v[234:235]
	v_pk_mul_f32 v[236:237], v[126:127], v[236:237]
	v_pk_mul_f32 v[120:121], v[120:121], v[234:235]
	v_pk_mul_f32 v[122:123], v[122:123], v[236:237]
	v_cvt_pk_bf16_f32 v120, v120, v121
	v_cvt_pk_bf16_f32 v121, v122, v123
	global_store_dwordx2 v[152:153], v[120:121], off
	v_pk_mul_f32 v[234:235], v[232:233], v[116:117] op_sel_hi:[0,1]
	v_pk_mul_f32 v[236:237], v[232:233], v[118:119] op_sel_hi:[0,1]
	v_exp_f32_e32 v234, v234
	v_exp_f32_e32 v235, v235
	v_exp_f32_e32 v236, v236
	v_exp_f32_e32 v237, v237
	v_pk_add_f32 v[234:235], v[234:235], 1.0 op_sel_hi:[1,0]
	v_pk_add_f32 v[236:237], v[236:237], 1.0 op_sel_hi:[1,0]
	v_rcp_f32_e32 v234, v234
	v_rcp_f32_e32 v235, v235
	v_rcp_f32_e32 v236, v236
	v_rcp_f32_e32 v237, v237
	v_pk_mul_f32 v[234:235], v[116:117], v[234:235]
	v_pk_mul_f32 v[236:237], v[118:119], v[236:237]
	v_pk_mul_f32 v[112:113], v[112:113], v[234:235]
	v_pk_mul_f32 v[114:115], v[114:115], v[236:237]
	v_cvt_pk_bf16_f32 v112, v112, v113
	v_cvt_pk_bf16_f32 v113, v114, v115
	global_store_dwordx2 v[152:153], v[112:113], off offset:128
	v_lshl_add_u64 v[152:153], v[152:153], 0, v[238:239]
	v_pk_mul_f32 v[234:235], v[232:233], v[108:109] op_sel_hi:[0,1]
	v_pk_mul_f32 v[236:237], v[232:233], v[110:111] op_sel_hi:[0,1]
	v_exp_f32_e32 v234, v234
	v_exp_f32_e32 v235, v235
	v_exp_f32_e32 v236, v236
	v_exp_f32_e32 v237, v237
	v_pk_add_f32 v[234:235], v[234:235], 1.0 op_sel_hi:[1,0]
	v_pk_add_f32 v[236:237], v[236:237], 1.0 op_sel_hi:[1,0]
	v_rcp_f32_e32 v234, v234
	v_rcp_f32_e32 v235, v235
	v_rcp_f32_e32 v236, v236
	v_rcp_f32_e32 v237, v237
	v_pk_mul_f32 v[234:235], v[108:109], v[234:235]
	v_pk_mul_f32 v[236:237], v[110:111], v[236:237]
	v_pk_mul_f32 v[104:105], v[104:105], v[234:235]
	v_pk_mul_f32 v[106:107], v[106:107], v[236:237]
	v_cvt_pk_bf16_f32 v104, v104, v105
	v_cvt_pk_bf16_f32 v105, v106, v107
	global_store_dwordx2 v[152:153], v[104:105], off
	v_pk_mul_f32 v[234:235], v[232:233], v[100:101] op_sel_hi:[0,1]
	v_pk_mul_f32 v[236:237], v[232:233], v[102:103] op_sel_hi:[0,1]
	v_exp_f32_e32 v234, v234
	v_exp_f32_e32 v235, v235
	v_exp_f32_e32 v236, v236
	v_exp_f32_e32 v237, v237
	v_pk_add_f32 v[234:235], v[234:235], 1.0 op_sel_hi:[1,0]
	v_pk_add_f32 v[236:237], v[236:237], 1.0 op_sel_hi:[1,0]
	v_rcp_f32_e32 v234, v234
	v_rcp_f32_e32 v235, v235
	v_rcp_f32_e32 v236, v236
	v_rcp_f32_e32 v237, v237
	v_pk_mul_f32 v[234:235], v[100:101], v[234:235]
	v_pk_mul_f32 v[236:237], v[102:103], v[236:237]
	v_pk_mul_f32 v[96:97], v[96:97], v[234:235]
	v_pk_mul_f32 v[98:99], v[98:99], v[236:237]
	v_cvt_pk_bf16_f32 v96, v96, v97
	v_cvt_pk_bf16_f32 v97, v98, v99
	global_store_dwordx2 v[152:153], v[96:97], off offset:128
	v_lshl_add_u64 v[152:153], v[152:153], 0, v[238:239]
	v_pk_mul_f32 v[234:235], v[232:233], v[92:93] op_sel_hi:[0,1]
	v_pk_mul_f32 v[236:237], v[232:233], v[94:95] op_sel_hi:[0,1]
	v_exp_f32_e32 v234, v234
	v_exp_f32_e32 v235, v235
	v_exp_f32_e32 v236, v236
	v_exp_f32_e32 v237, v237
	v_pk_add_f32 v[234:235], v[234:235], 1.0 op_sel_hi:[1,0]
	v_pk_add_f32 v[236:237], v[236:237], 1.0 op_sel_hi:[1,0]
	v_rcp_f32_e32 v234, v234
	v_rcp_f32_e32 v235, v235
	v_rcp_f32_e32 v236, v236
	v_rcp_f32_e32 v237, v237
	v_pk_mul_f32 v[234:235], v[92:93], v[234:235]
	v_pk_mul_f32 v[236:237], v[94:95], v[236:237]
	v_pk_mul_f32 v[88:89], v[88:89], v[234:235]
	v_pk_mul_f32 v[90:91], v[90:91], v[236:237]
	v_cvt_pk_bf16_f32 v88, v88, v89
	v_cvt_pk_bf16_f32 v89, v90, v91
	global_store_dwordx2 v[152:153], v[88:89], off
	v_pk_mul_f32 v[234:235], v[232:233], v[84:85] op_sel_hi:[0,1]
	v_pk_mul_f32 v[236:237], v[232:233], v[86:87] op_sel_hi:[0,1]
	v_exp_f32_e32 v234, v234
	v_exp_f32_e32 v235, v235
	v_exp_f32_e32 v236, v236
	v_exp_f32_e32 v237, v237
	v_pk_add_f32 v[234:235], v[234:235], 1.0 op_sel_hi:[1,0]
	v_pk_add_f32 v[236:237], v[236:237], 1.0 op_sel_hi:[1,0]
	v_rcp_f32_e32 v234, v234
	v_rcp_f32_e32 v235, v235
	v_rcp_f32_e32 v236, v236
	v_rcp_f32_e32 v237, v237
	v_pk_mul_f32 v[234:235], v[84:85], v[234:235]
	v_pk_mul_f32 v[236:237], v[86:87], v[236:237]
	v_pk_mul_f32 v[80:81], v[80:81], v[234:235]
	v_pk_mul_f32 v[82:83], v[82:83], v[236:237]
	v_cvt_pk_bf16_f32 v80, v80, v81
	v_cvt_pk_bf16_f32 v81, v82, v83
	global_store_dwordx2 v[152:153], v[80:81], off offset:128
	v_lshl_add_u64 v[152:153], v[152:153], 0, v[238:239]
	v_pk_mul_f32 v[234:235], v[232:233], v[76:77] op_sel_hi:[0,1]
	v_pk_mul_f32 v[236:237], v[232:233], v[78:79] op_sel_hi:[0,1]
	v_exp_f32_e32 v234, v234
	v_exp_f32_e32 v235, v235
	v_exp_f32_e32 v236, v236
	v_exp_f32_e32 v237, v237
	v_pk_add_f32 v[234:235], v[234:235], 1.0 op_sel_hi:[1,0]
	v_pk_add_f32 v[236:237], v[236:237], 1.0 op_sel_hi:[1,0]
	v_rcp_f32_e32 v234, v234
	v_rcp_f32_e32 v235, v235
	v_rcp_f32_e32 v236, v236
	v_rcp_f32_e32 v237, v237
	v_pk_mul_f32 v[234:235], v[76:77], v[234:235]
	v_pk_mul_f32 v[236:237], v[78:79], v[236:237]
	v_pk_mul_f32 v[72:73], v[72:73], v[234:235]
	v_pk_mul_f32 v[74:75], v[74:75], v[236:237]
	v_cvt_pk_bf16_f32 v72, v72, v73
	v_cvt_pk_bf16_f32 v73, v74, v75
	global_store_dwordx2 v[152:153], v[72:73], off
	v_pk_mul_f32 v[234:235], v[232:233], v[68:69] op_sel_hi:[0,1]
	v_pk_mul_f32 v[236:237], v[232:233], v[70:71] op_sel_hi:[0,1]
	v_exp_f32_e32 v234, v234
	v_exp_f32_e32 v235, v235
	v_exp_f32_e32 v236, v236
	v_exp_f32_e32 v237, v237
	v_pk_add_f32 v[234:235], v[234:235], 1.0 op_sel_hi:[1,0]
	v_pk_add_f32 v[236:237], v[236:237], 1.0 op_sel_hi:[1,0]
	v_rcp_f32_e32 v234, v234
	v_rcp_f32_e32 v235, v235
	v_rcp_f32_e32 v236, v236
	v_rcp_f32_e32 v237, v237
	v_pk_mul_f32 v[234:235], v[68:69], v[234:235]
	v_pk_mul_f32 v[236:237], v[70:71], v[236:237]
	v_pk_mul_f32 v[64:65], v[64:65], v[234:235]
	v_pk_mul_f32 v[66:67], v[66:67], v[236:237]
	v_cvt_pk_bf16_f32 v64, v64, v65
	v_cvt_pk_bf16_f32 v65, v66, v67
	global_store_dwordx2 v[152:153], v[64:65], off offset:128
	v_lshl_add_u64 v[152:153], v[152:153], 0, v[240:241]
	v_pk_mul_f32 v[234:235], v[232:233], v[60:61] op_sel_hi:[0,1]
	v_pk_mul_f32 v[236:237], v[232:233], v[62:63] op_sel_hi:[0,1]
	v_exp_f32_e32 v234, v234
	v_exp_f32_e32 v235, v235
	v_exp_f32_e32 v236, v236
	v_exp_f32_e32 v237, v237
	v_pk_add_f32 v[234:235], v[234:235], 1.0 op_sel_hi:[1,0]
	v_pk_add_f32 v[236:237], v[236:237], 1.0 op_sel_hi:[1,0]
	v_rcp_f32_e32 v234, v234
	v_rcp_f32_e32 v235, v235
	v_rcp_f32_e32 v236, v236
	v_rcp_f32_e32 v237, v237
	v_pk_mul_f32 v[234:235], v[60:61], v[234:235]
	v_pk_mul_f32 v[236:237], v[62:63], v[236:237]
	v_pk_mul_f32 v[56:57], v[56:57], v[234:235]
	v_pk_mul_f32 v[58:59], v[58:59], v[236:237]
	v_cvt_pk_bf16_f32 v56, v56, v57
	v_cvt_pk_bf16_f32 v57, v58, v59
	global_store_dwordx2 v[152:153], v[56:57], off
	v_pk_mul_f32 v[234:235], v[232:233], v[52:53] op_sel_hi:[0,1]
	v_pk_mul_f32 v[236:237], v[232:233], v[54:55] op_sel_hi:[0,1]
	v_exp_f32_e32 v234, v234
	v_exp_f32_e32 v235, v235
	v_exp_f32_e32 v236, v236
	v_exp_f32_e32 v237, v237
	v_pk_add_f32 v[234:235], v[234:235], 1.0 op_sel_hi:[1,0]
	v_pk_add_f32 v[236:237], v[236:237], 1.0 op_sel_hi:[1,0]
	v_rcp_f32_e32 v234, v234
	v_rcp_f32_e32 v235, v235
	v_rcp_f32_e32 v236, v236
	v_rcp_f32_e32 v237, v237
	v_pk_mul_f32 v[234:235], v[52:53], v[234:235]
	v_pk_mul_f32 v[236:237], v[54:55], v[236:237]
	v_pk_mul_f32 v[48:49], v[48:49], v[234:235]
	v_pk_mul_f32 v[50:51], v[50:51], v[236:237]
	v_cvt_pk_bf16_f32 v48, v48, v49
	v_cvt_pk_bf16_f32 v49, v50, v51
	global_store_dwordx2 v[152:153], v[48:49], off offset:128
	v_lshl_add_u64 v[152:153], v[152:153], 0, v[238:239]
	v_pk_mul_f32 v[234:235], v[232:233], v[44:45] op_sel_hi:[0,1]
	v_pk_mul_f32 v[236:237], v[232:233], v[46:47] op_sel_hi:[0,1]
	v_exp_f32_e32 v234, v234
	v_exp_f32_e32 v235, v235
	v_exp_f32_e32 v236, v236
	v_exp_f32_e32 v237, v237
	v_pk_add_f32 v[234:235], v[234:235], 1.0 op_sel_hi:[1,0]
	v_pk_add_f32 v[236:237], v[236:237], 1.0 op_sel_hi:[1,0]
	v_rcp_f32_e32 v234, v234
	v_rcp_f32_e32 v235, v235
	v_rcp_f32_e32 v236, v236
	v_rcp_f32_e32 v237, v237
	v_pk_mul_f32 v[234:235], v[44:45], v[234:235]
	v_pk_mul_f32 v[236:237], v[46:47], v[236:237]
	v_pk_mul_f32 v[40:41], v[40:41], v[234:235]
	v_pk_mul_f32 v[42:43], v[42:43], v[236:237]
	v_cvt_pk_bf16_f32 v40, v40, v41
	v_cvt_pk_bf16_f32 v41, v42, v43
	global_store_dwordx2 v[152:153], v[40:41], off
	v_pk_mul_f32 v[234:235], v[232:233], v[36:37] op_sel_hi:[0,1]
	v_pk_mul_f32 v[236:237], v[232:233], v[38:39] op_sel_hi:[0,1]
	v_exp_f32_e32 v234, v234
	v_exp_f32_e32 v235, v235
	v_exp_f32_e32 v236, v236
	v_exp_f32_e32 v237, v237
	v_pk_add_f32 v[234:235], v[234:235], 1.0 op_sel_hi:[1,0]
	v_pk_add_f32 v[236:237], v[236:237], 1.0 op_sel_hi:[1,0]
	v_rcp_f32_e32 v234, v234
	v_rcp_f32_e32 v235, v235
	v_rcp_f32_e32 v236, v236
	v_rcp_f32_e32 v237, v237
	v_pk_mul_f32 v[234:235], v[36:37], v[234:235]
	v_pk_mul_f32 v[236:237], v[38:39], v[236:237]
	v_pk_mul_f32 v[32:33], v[32:33], v[234:235]
	v_pk_mul_f32 v[34:35], v[34:35], v[236:237]
	v_cvt_pk_bf16_f32 v32, v32, v33
	v_cvt_pk_bf16_f32 v33, v34, v35
	global_store_dwordx2 v[152:153], v[32:33], off offset:128
	v_lshl_add_u64 v[152:153], v[152:153], 0, v[238:239]
	v_pk_mul_f32 v[234:235], v[232:233], v[28:29] op_sel_hi:[0,1]
	v_pk_mul_f32 v[236:237], v[232:233], v[30:31] op_sel_hi:[0,1]
	v_exp_f32_e32 v234, v234
	v_exp_f32_e32 v235, v235
	v_exp_f32_e32 v236, v236
	v_exp_f32_e32 v237, v237
	v_pk_add_f32 v[234:235], v[234:235], 1.0 op_sel_hi:[1,0]
	v_pk_add_f32 v[236:237], v[236:237], 1.0 op_sel_hi:[1,0]
	v_rcp_f32_e32 v234, v234
	v_rcp_f32_e32 v235, v235
	v_rcp_f32_e32 v236, v236
	v_rcp_f32_e32 v237, v237
	v_pk_mul_f32 v[234:235], v[28:29], v[234:235]
	v_pk_mul_f32 v[236:237], v[30:31], v[236:237]
	v_pk_mul_f32 v[24:25], v[24:25], v[234:235]
	v_pk_mul_f32 v[26:27], v[26:27], v[236:237]
	v_cvt_pk_bf16_f32 v24, v24, v25
	v_cvt_pk_bf16_f32 v25, v26, v27
	global_store_dwordx2 v[152:153], v[24:25], off
	v_pk_mul_f32 v[234:235], v[232:233], v[20:21] op_sel_hi:[0,1]
	v_pk_mul_f32 v[236:237], v[232:233], v[22:23] op_sel_hi:[0,1]
	v_exp_f32_e32 v234, v234
	v_exp_f32_e32 v235, v235
	v_exp_f32_e32 v236, v236
	v_exp_f32_e32 v237, v237
	v_pk_add_f32 v[234:235], v[234:235], 1.0 op_sel_hi:[1,0]
	v_pk_add_f32 v[236:237], v[236:237], 1.0 op_sel_hi:[1,0]
	v_rcp_f32_e32 v234, v234
	v_rcp_f32_e32 v235, v235
	v_rcp_f32_e32 v236, v236
	v_rcp_f32_e32 v237, v237
	v_pk_mul_f32 v[234:235], v[20:21], v[234:235]
	v_pk_mul_f32 v[236:237], v[22:23], v[236:237]
	v_pk_mul_f32 v[16:17], v[16:17], v[234:235]
	v_pk_mul_f32 v[18:19], v[18:19], v[236:237]
	v_cvt_pk_bf16_f32 v16, v16, v17
	v_cvt_pk_bf16_f32 v17, v18, v19
	global_store_dwordx2 v[152:153], v[16:17], off offset:128
	v_lshl_add_u64 v[152:153], v[152:153], 0, v[238:239]
	v_pk_mul_f32 v[234:235], v[232:233], v[12:13] op_sel_hi:[0,1]
	v_pk_mul_f32 v[236:237], v[232:233], v[14:15] op_sel_hi:[0,1]
	v_exp_f32_e32 v234, v234
	v_exp_f32_e32 v235, v235
	v_exp_f32_e32 v236, v236
	v_exp_f32_e32 v237, v237
	v_pk_add_f32 v[234:235], v[234:235], 1.0 op_sel_hi:[1,0]
	v_pk_add_f32 v[236:237], v[236:237], 1.0 op_sel_hi:[1,0]
	v_rcp_f32_e32 v234, v234
	v_rcp_f32_e32 v235, v235
	v_rcp_f32_e32 v236, v236
	v_rcp_f32_e32 v237, v237
	v_pk_mul_f32 v[234:235], v[12:13], v[234:235]
	v_pk_mul_f32 v[236:237], v[14:15], v[236:237]
	v_pk_mul_f32 v[8:9], v[8:9], v[234:235]
	v_pk_mul_f32 v[10:11], v[10:11], v[236:237]
	v_cvt_pk_bf16_f32 v8, v8, v9
	v_cvt_pk_bf16_f32 v9, v10, v11
	global_store_dwordx2 v[152:153], v[8:9], off
	v_pk_mul_f32 v[234:235], v[232:233], v[4:5] op_sel_hi:[0,1]
	v_pk_mul_f32 v[236:237], v[232:233], v[6:7] op_sel_hi:[0,1]
	v_exp_f32_e32 v234, v234
	v_exp_f32_e32 v235, v235
	v_exp_f32_e32 v236, v236
	v_exp_f32_e32 v237, v237
	v_pk_add_f32 v[234:235], v[234:235], 1.0 op_sel_hi:[1,0]
	v_pk_add_f32 v[236:237], v[236:237], 1.0 op_sel_hi:[1,0]
	v_rcp_f32_e32 v234, v234
	v_rcp_f32_e32 v235, v235
	v_rcp_f32_e32 v236, v236
	v_rcp_f32_e32 v237, v237
	v_pk_mul_f32 v[234:235], v[4:5], v[234:235]
	v_pk_mul_f32 v[236:237], v[6:7], v[236:237]
	v_pk_mul_f32 v[0:1], v[0:1], v[234:235]
	v_pk_mul_f32 v[2:3], v[2:3], v[236:237]
	v_cvt_pk_bf16_f32 v0, v0, v1
	v_cvt_pk_bf16_f32 v1, v2, v3
	global_store_dwordx2 v[152:153], v[0:1], off offset:128
	s_andn2_b64 vcc, exec, s[10:11]
	s_mov_b64 s[10:11], -1
	s_cbranch_vccnz .LBB0_947
	s_andn2_b64 vcc, exec, s[0:1]
	s_cbranch_vccnz .LBB0_946
	s_barrier
	s_branch .LBB0_946

.LBB0_1437:
	v_lshl_or_b32 v142, s65, 7, v146
	v_lshl_add_u32 v150, s44, 8, v144
	v_ashrrev_i32_e32 v143, 31, v142
	v_mov_b64_e32 v[140:141], s[22:23]
	v_mad_i64_i32 v[152:153], s[46:47], v150, s64, v[140:141]
	v_lshlrev_b64 v[142:143], 1, v[142:143]
	v_lshl_add_u64 v[152:153], v[152:153], 0, v[142:143]
	v_mov_b32_e32 v232, 0xbfb8aa3b
	v_mov_b64_e32 v[238:239], 0x16000
	v_mov_b64_e32 v[240:241], 0x6e000
	v_pk_mul_f32 v[234:235], v[232:233], v[124:125] op_sel_hi:[0,1]
	v_pk_mul_f32 v[236:237], v[232:233], v[126:127] op_sel_hi:[0,1]
	v_exp_f32_e32 v234, v234
	v_exp_f32_e32 v235, v235
	v_exp_f32_e32 v236, v236
	v_exp_f32_e32 v237, v237
	v_pk_add_f32 v[234:235], v[234:235], 1.0 op_sel_hi:[1,0]
	v_pk_add_f32 v[236:237], v[236:237], 1.0 op_sel_hi:[1,0]
	v_rcp_f32_e32 v234, v234
	v_rcp_f32_e32 v235, v235
	v_rcp_f32_e32 v236, v236
	v_rcp_f32_e32 v237, v237
	v_pk_mul_f32 v[234:235], v[124:125], v[234:235]
	v_pk_mul_f32 v[236:237], v[126:127], v[236:237]
	v_pk_mul_f32 v[120:121], v[120:121], v[234:235]
	v_pk_mul_f32 v[122:123], v[122:123], v[236:237]
	v_cvt_pk_bf16_f32 v120, v120, v121
	v_cvt_pk_bf16_f32 v121, v122, v123
	global_store_dwordx2 v[152:153], v[120:121], off
	v_pk_mul_f32 v[234:235], v[232:233], v[116:117] op_sel_hi:[0,1]
	v_pk_mul_f32 v[236:237], v[232:233], v[118:119] op_sel_hi:[0,1]
	v_exp_f32_e32 v234, v234
	v_exp_f32_e32 v235, v235
	v_exp_f32_e32 v236, v236
	v_exp_f32_e32 v237, v237
	v_pk_add_f32 v[234:235], v[234:235], 1.0 op_sel_hi:[1,0]
	v_pk_add_f32 v[236:237], v[236:237], 1.0 op_sel_hi:[1,0]
	v_rcp_f32_e32 v234, v234
	v_rcp_f32_e32 v235, v235
	v_rcp_f32_e32 v236, v236
	v_rcp_f32_e32 v237, v237
	v_pk_mul_f32 v[234:235], v[116:117], v[234:235]
	v_pk_mul_f32 v[236:237], v[118:119], v[236:237]
	v_pk_mul_f32 v[112:113], v[112:113], v[234:235]
	v_pk_mul_f32 v[114:115], v[114:115], v[236:237]
	v_cvt_pk_bf16_f32 v112, v112, v113
	v_cvt_pk_bf16_f32 v113, v114, v115
	global_store_dwordx2 v[152:153], v[112:113], off offset:128
	v_lshl_add_u64 v[152:153], v[152:153], 0, v[238:239]
	v_pk_mul_f32 v[234:235], v[232:233], v[108:109] op_sel_hi:[0,1]
	v_pk_mul_f32 v[236:237], v[232:233], v[110:111] op_sel_hi:[0,1]
	v_exp_f32_e32 v234, v234
	v_exp_f32_e32 v235, v235
	v_exp_f32_e32 v236, v236
	v_exp_f32_e32 v237, v237
	v_pk_add_f32 v[234:235], v[234:235], 1.0 op_sel_hi:[1,0]
	v_pk_add_f32 v[236:237], v[236:237], 1.0 op_sel_hi:[1,0]
	v_rcp_f32_e32 v234, v234
	v_rcp_f32_e32 v235, v235
	v_rcp_f32_e32 v236, v236
	v_rcp_f32_e32 v237, v237
	v_pk_mul_f32 v[234:235], v[108:109], v[234:235]
	v_pk_mul_f32 v[236:237], v[110:111], v[236:237]
	v_pk_mul_f32 v[104:105], v[104:105], v[234:235]
	v_pk_mul_f32 v[106:107], v[106:107], v[236:237]
	v_cvt_pk_bf16_f32 v104, v104, v105
	v_cvt_pk_bf16_f32 v105, v106, v107
	global_store_dwordx2 v[152:153], v[104:105], off
	v_pk_mul_f32 v[234:235], v[232:233], v[100:101] op_sel_hi:[0,1]
	v_pk_mul_f32 v[236:237], v[232:233], v[102:103] op_sel_hi:[0,1]
	v_exp_f32_e32 v234, v234
	v_exp_f32_e32 v235, v235
	v_exp_f32_e32 v236, v236
	v_exp_f32_e32 v237, v237
	v_pk_add_f32 v[234:235], v[234:235], 1.0 op_sel_hi:[1,0]
	v_pk_add_f32 v[236:237], v[236:237], 1.0 op_sel_hi:[1,0]
	v_rcp_f32_e32 v234, v234
	v_rcp_f32_e32 v235, v235
	v_rcp_f32_e32 v236, v236
	v_rcp_f32_e32 v237, v237
	v_pk_mul_f32 v[234:235], v[100:101], v[234:235]
	v_pk_mul_f32 v[236:237], v[102:103], v[236:237]
	v_pk_mul_f32 v[96:97], v[96:97], v[234:235]
	v_pk_mul_f32 v[98:99], v[98:99], v[236:237]
	v_cvt_pk_bf16_f32 v96, v96, v97
	v_cvt_pk_bf16_f32 v97, v98, v99
	global_store_dwordx2 v[152:153], v[96:97], off offset:128
	v_lshl_add_u64 v[152:153], v[152:153], 0, v[238:239]
	v_pk_mul_f32 v[234:235], v[232:233], v[92:93] op_sel_hi:[0,1]
	v_pk_mul_f32 v[236:237], v[232:233], v[94:95] op_sel_hi:[0,1]
	v_exp_f32_e32 v234, v234
	v_exp_f32_e32 v235, v235
	v_exp_f32_e32 v236, v236
	v_exp_f32_e32 v237, v237
	v_pk_add_f32 v[234:235], v[234:235], 1.0 op_sel_hi:[1,0]
	v_pk_add_f32 v[236:237], v[236:237], 1.0 op_sel_hi:[1,0]
	v_rcp_f32_e32 v234, v234
	v_rcp_f32_e32 v235, v235
	v_rcp_f32_e32 v236, v236
	v_rcp_f32_e32 v237, v237
	v_pk_mul_f32 v[234:235], v[92:93], v[234:235]
	v_pk_mul_f32 v[236:237], v[94:95], v[236:237]
	v_pk_mul_f32 v[88:89], v[88:89], v[234:235]
	v_pk_mul_f32 v[90:91], v[90:91], v[236:237]
	v_cvt_pk_bf16_f32 v88, v88, v89
	v_cvt_pk_bf16_f32 v89, v90, v91
	global_store_dwordx2 v[152:153], v[88:89], off
	v_pk_mul_f32 v[234:235], v[232:233], v[84:85] op_sel_hi:[0,1]
	v_pk_mul_f32 v[236:237], v[232:233], v[86:87] op_sel_hi:[0,1]
	v_exp_f32_e32 v234, v234
	v_exp_f32_e32 v235, v235
	v_exp_f32_e32 v236, v236
	v_exp_f32_e32 v237, v237
	v_pk_add_f32 v[234:235], v[234:235], 1.0 op_sel_hi:[1,0]
	v_pk_add_f32 v[236:237], v[236:237], 1.0 op_sel_hi:[1,0]
	v_rcp_f32_e32 v234, v234
	v_rcp_f32_e32 v235, v235
	v_rcp_f32_e32 v236, v236
	v_rcp_f32_e32 v237, v237
	v_pk_mul_f32 v[234:235], v[84:85], v[234:235]
	v_pk_mul_f32 v[236:237], v[86:87], v[236:237]
	v_pk_mul_f32 v[80:81], v[80:81], v[234:235]
	v_pk_mul_f32 v[82:83], v[82:83], v[236:237]
	v_cvt_pk_bf16_f32 v80, v80, v81
	v_cvt_pk_bf16_f32 v81, v82, v83
	global_store_dwordx2 v[152:153], v[80:81], off offset:128
	v_lshl_add_u64 v[152:153], v[152:153], 0, v[238:239]
	v_pk_mul_f32 v[234:235], v[232:233], v[76:77] op_sel_hi:[0,1]
	v_pk_mul_f32 v[236:237], v[232:233], v[78:79] op_sel_hi:[0,1]
	v_exp_f32_e32 v234, v234
	v_exp_f32_e32 v235, v235
	v_exp_f32_e32 v236, v236
	v_exp_f32_e32 v237, v237
	v_pk_add_f32 v[234:235], v[234:235], 1.0 op_sel_hi:[1,0]
	v_pk_add_f32 v[236:237], v[236:237], 1.0 op_sel_hi:[1,0]
	v_rcp_f32_e32 v234, v234
	v_rcp_f32_e32 v235, v235
	v_rcp_f32_e32 v236, v236
	v_rcp_f32_e32 v237, v237
	v_pk_mul_f32 v[234:235], v[76:77], v[234:235]
	v_pk_mul_f32 v[236:237], v[78:79], v[236:237]
	v_pk_mul_f32 v[72:73], v[72:73], v[234:235]
	v_pk_mul_f32 v[74:75], v[74:75], v[236:237]
	v_cvt_pk_bf16_f32 v72, v72, v73
	v_cvt_pk_bf16_f32 v73, v74, v75
	global_store_dwordx2 v[152:153], v[72:73], off
	v_pk_mul_f32 v[234:235], v[232:233], v[68:69] op_sel_hi:[0,1]
	v_pk_mul_f32 v[236:237], v[232:233], v[70:71] op_sel_hi:[0,1]
	v_exp_f32_e32 v234, v234
	v_exp_f32_e32 v235, v235
	v_exp_f32_e32 v236, v236
	v_exp_f32_e32 v237, v237
	v_pk_add_f32 v[234:235], v[234:235], 1.0 op_sel_hi:[1,0]
	v_pk_add_f32 v[236:237], v[236:237], 1.0 op_sel_hi:[1,0]
	v_rcp_f32_e32 v234, v234
	v_rcp_f32_e32 v235, v235
	v_rcp_f32_e32 v236, v236
	v_rcp_f32_e32 v237, v237
	v_pk_mul_f32 v[234:235], v[68:69], v[234:235]
	v_pk_mul_f32 v[236:237], v[70:71], v[236:237]
	v_pk_mul_f32 v[64:65], v[64:65], v[234:235]
	v_pk_mul_f32 v[66:67], v[66:67], v[236:237]
	v_cvt_pk_bf16_f32 v64, v64, v65
	v_cvt_pk_bf16_f32 v65, v66, v67
	global_store_dwordx2 v[152:153], v[64:65], off offset:128
	v_lshl_add_u64 v[152:153], v[152:153], 0, v[240:241]
	v_pk_mul_f32 v[234:235], v[232:233], v[60:61] op_sel_hi:[0,1]
	v_pk_mul_f32 v[236:237], v[232:233], v[62:63] op_sel_hi:[0,1]
	v_exp_f32_e32 v234, v234
	v_exp_f32_e32 v235, v235
	v_exp_f32_e32 v236, v236
	v_exp_f32_e32 v237, v237
	v_pk_add_f32 v[234:235], v[234:235], 1.0 op_sel_hi:[1,0]
	v_pk_add_f32 v[236:237], v[236:237], 1.0 op_sel_hi:[1,0]
	v_rcp_f32_e32 v234, v234
	v_rcp_f32_e32 v235, v235
	v_rcp_f32_e32 v236, v236
	v_rcp_f32_e32 v237, v237
	v_pk_mul_f32 v[234:235], v[60:61], v[234:235]
	v_pk_mul_f32 v[236:237], v[62:63], v[236:237]
	v_pk_mul_f32 v[56:57], v[56:57], v[234:235]
	v_pk_mul_f32 v[58:59], v[58:59], v[236:237]
	v_cvt_pk_bf16_f32 v56, v56, v57
	v_cvt_pk_bf16_f32 v57, v58, v59
	global_store_dwordx2 v[152:153], v[56:57], off
	v_pk_mul_f32 v[234:235], v[232:233], v[52:53] op_sel_hi:[0,1]
	v_pk_mul_f32 v[236:237], v[232:233], v[54:55] op_sel_hi:[0,1]
	v_exp_f32_e32 v234, v234
	v_exp_f32_e32 v235, v235
	v_exp_f32_e32 v236, v236
	v_exp_f32_e32 v237, v237
	v_pk_add_f32 v[234:235], v[234:235], 1.0 op_sel_hi:[1,0]
	v_pk_add_f32 v[236:237], v[236:237], 1.0 op_sel_hi:[1,0]
	v_rcp_f32_e32 v234, v234
	v_rcp_f32_e32 v235, v235
	v_rcp_f32_e32 v236, v236
	v_rcp_f32_e32 v237, v237
	v_pk_mul_f32 v[234:235], v[52:53], v[234:235]
	v_pk_mul_f32 v[236:237], v[54:55], v[236:237]
	v_pk_mul_f32 v[48:49], v[48:49], v[234:235]
	v_pk_mul_f32 v[50:51], v[50:51], v[236:237]
	v_cvt_pk_bf16_f32 v48, v48, v49
	v_cvt_pk_bf16_f32 v49, v50, v51
	global_store_dwordx2 v[152:153], v[48:49], off offset:128
	v_lshl_add_u64 v[152:153], v[152:153], 0, v[238:239]
	v_pk_mul_f32 v[234:235], v[232:233], v[44:45] op_sel_hi:[0,1]
	v_pk_mul_f32 v[236:237], v[232:233], v[46:47] op_sel_hi:[0,1]
	v_exp_f32_e32 v234, v234
	v_exp_f32_e32 v235, v235
	v_exp_f32_e32 v236, v236
	v_exp_f32_e32 v237, v237
	v_pk_add_f32 v[234:235], v[234:235], 1.0 op_sel_hi:[1,0]
	v_pk_add_f32 v[236:237], v[236:237], 1.0 op_sel_hi:[1,0]
	v_rcp_f32_e32 v234, v234
	v_rcp_f32_e32 v235, v235
	v_rcp_f32_e32 v236, v236
	v_rcp_f32_e32 v237, v237
	v_pk_mul_f32 v[234:235], v[44:45], v[234:235]
	v_pk_mul_f32 v[236:237], v[46:47], v[236:237]
	v_pk_mul_f32 v[40:41], v[40:41], v[234:235]
	v_pk_mul_f32 v[42:43], v[42:43], v[236:237]
	v_cvt_pk_bf16_f32 v40, v40, v41
	v_cvt_pk_bf16_f32 v41, v42, v43
	global_store_dwordx2 v[152:153], v[40:41], off
	v_pk_mul_f32 v[234:235], v[232:233], v[36:37] op_sel_hi:[0,1]
	v_pk_mul_f32 v[236:237], v[232:233], v[38:39] op_sel_hi:[0,1]
	v_exp_f32_e32 v234, v234
	v_exp_f32_e32 v235, v235
	v_exp_f32_e32 v236, v236
	v_exp_f32_e32 v237, v237
	v_pk_add_f32 v[234:235], v[234:235], 1.0 op_sel_hi:[1,0]
	v_pk_add_f32 v[236:237], v[236:237], 1.0 op_sel_hi:[1,0]
	v_rcp_f32_e32 v234, v234
	v_rcp_f32_e32 v235, v235
	v_rcp_f32_e32 v236, v236
	v_rcp_f32_e32 v237, v237
	v_pk_mul_f32 v[234:235], v[36:37], v[234:235]
	v_pk_mul_f32 v[236:237], v[38:39], v[236:237]
	v_pk_mul_f32 v[32:33], v[32:33], v[234:235]
	v_pk_mul_f32 v[34:35], v[34:35], v[236:237]
	v_cvt_pk_bf16_f32 v32, v32, v33
	v_cvt_pk_bf16_f32 v33, v34, v35
	global_store_dwordx2 v[152:153], v[32:33], off offset:128
	v_lshl_add_u64 v[152:153], v[152:153], 0, v[238:239]
	v_pk_mul_f32 v[234:235], v[232:233], v[28:29] op_sel_hi:[0,1]
	v_pk_mul_f32 v[236:237], v[232:233], v[30:31] op_sel_hi:[0,1]
	v_exp_f32_e32 v234, v234
	v_exp_f32_e32 v235, v235
	v_exp_f32_e32 v236, v236
	v_exp_f32_e32 v237, v237
	v_pk_add_f32 v[234:235], v[234:235], 1.0 op_sel_hi:[1,0]
	v_pk_add_f32 v[236:237], v[236:237], 1.0 op_sel_hi:[1,0]
	v_rcp_f32_e32 v234, v234
	v_rcp_f32_e32 v235, v235
	v_rcp_f32_e32 v236, v236
	v_rcp_f32_e32 v237, v237
	v_pk_mul_f32 v[234:235], v[28:29], v[234:235]
	v_pk_mul_f32 v[236:237], v[30:31], v[236:237]
	v_pk_mul_f32 v[24:25], v[24:25], v[234:235]
	v_pk_mul_f32 v[26:27], v[26:27], v[236:237]
	v_cvt_pk_bf16_f32 v24, v24, v25
	v_cvt_pk_bf16_f32 v25, v26, v27
	global_store_dwordx2 v[152:153], v[24:25], off
	v_pk_mul_f32 v[234:235], v[232:233], v[20:21] op_sel_hi:[0,1]
	v_pk_mul_f32 v[236:237], v[232:233], v[22:23] op_sel_hi:[0,1]
	v_exp_f32_e32 v234, v234
	v_exp_f32_e32 v235, v235
	v_exp_f32_e32 v236, v236
	v_exp_f32_e32 v237, v237
	v_pk_add_f32 v[234:235], v[234:235], 1.0 op_sel_hi:[1,0]
	v_pk_add_f32 v[236:237], v[236:237], 1.0 op_sel_hi:[1,0]
	v_rcp_f32_e32 v234, v234
	v_rcp_f32_e32 v235, v235
	v_rcp_f32_e32 v236, v236
	v_rcp_f32_e32 v237, v237
	v_pk_mul_f32 v[234:235], v[20:21], v[234:235]
	v_pk_mul_f32 v[236:237], v[22:23], v[236:237]
	v_pk_mul_f32 v[16:17], v[16:17], v[234:235]
	v_pk_mul_f32 v[18:19], v[18:19], v[236:237]
	v_cvt_pk_bf16_f32 v16, v16, v17
	v_cvt_pk_bf16_f32 v17, v18, v19
	global_store_dwordx2 v[152:153], v[16:17], off offset:128
	v_lshl_add_u64 v[152:153], v[152:153], 0, v[238:239]
	v_pk_mul_f32 v[234:235], v[232:233], v[12:13] op_sel_hi:[0,1]
	v_pk_mul_f32 v[236:237], v[232:233], v[14:15] op_sel_hi:[0,1]
	v_exp_f32_e32 v234, v234
	v_exp_f32_e32 v235, v235
	v_exp_f32_e32 v236, v236
	v_exp_f32_e32 v237, v237
	v_pk_add_f32 v[234:235], v[234:235], 1.0 op_sel_hi:[1,0]
	v_pk_add_f32 v[236:237], v[236:237], 1.0 op_sel_hi:[1,0]
	v_rcp_f32_e32 v234, v234
	v_rcp_f32_e32 v235, v235
	v_rcp_f32_e32 v236, v236
	v_rcp_f32_e32 v237, v237
	v_pk_mul_f32 v[234:235], v[12:13], v[234:235]
	v_pk_mul_f32 v[236:237], v[14:15], v[236:237]
	v_pk_mul_f32 v[8:9], v[8:9], v[234:235]
	v_pk_mul_f32 v[10:11], v[10:11], v[236:237]
	v_cvt_pk_bf16_f32 v8, v8, v9
	v_cvt_pk_bf16_f32 v9, v10, v11
	global_store_dwordx2 v[152:153], v[8:9], off
	v_pk_mul_f32 v[234:235], v[232:233], v[4:5] op_sel_hi:[0,1]
	v_pk_mul_f32 v[236:237], v[232:233], v[6:7] op_sel_hi:[0,1]
	v_exp_f32_e32 v234, v234
	v_exp_f32_e32 v235, v235
	v_exp_f32_e32 v236, v236
	v_exp_f32_e32 v237, v237
	v_pk_add_f32 v[234:235], v[234:235], 1.0 op_sel_hi:[1,0]
	v_pk_add_f32 v[236:237], v[236:237], 1.0 op_sel_hi:[1,0]
	v_rcp_f32_e32 v234, v234
	v_rcp_f32_e32 v235, v235
	v_rcp_f32_e32 v236, v236
	v_rcp_f32_e32 v237, v237
	v_pk_mul_f32 v[234:235], v[4:5], v[234:235]
	v_pk_mul_f32 v[236:237], v[6:7], v[236:237]
	v_pk_mul_f32 v[0:1], v[0:1], v[234:235]
	v_pk_mul_f32 v[2:3], v[2:3], v[236:237]
	v_cvt_pk_bf16_f32 v0, v0, v1
	v_cvt_pk_bf16_f32 v1, v2, v3
	global_store_dwordx2 v[152:153], v[0:1], off offset:128
	s_andn2_b64 vcc, exec, s[8:9]
	s_mov_b64 s[8:9], -1
	s_cbranch_vccnz .LBB0_1430
	s_andn2_b64 vcc, exec, s[0:1]
	s_cbranch_vccnz .LBB0_1429
	s_barrier
	s_branch .LBB0_1429

	.amdhsa_kernel _Z8yoco_fwd4Args
		.amdhsa_group_segment_fixed_size 0
		.amdhsa_private_segment_fixed_size 0
		.amdhsa_kernarg_size 376
		.amdhsa_user_sgpr_count 2
		.amdhsa_user_sgpr_dispatch_ptr 0
		.amdhsa_user_sgpr_queue_ptr 0
		.amdhsa_user_sgpr_kernarg_segment_ptr 1
		.amdhsa_user_sgpr_dispatch_id 0
		.amdhsa_user_sgpr_kernarg_preload_length 0
		.amdhsa_user_sgpr_kernarg_preload_offset 0
		.amdhsa_user_sgpr_private_segment_size 0
		.amdhsa_uses_dynamic_stack 0
		.amdhsa_enable_private_segment 0
		.amdhsa_system_sgpr_workgroup_id_x 1
		.amdhsa_system_sgpr_workgroup_id_y 0
		.amdhsa_system_sgpr_workgroup_id_z 0
		.amdhsa_system_sgpr_workgroup_info 0
		.amdhsa_system_vgpr_workitem_id 2
		.amdhsa_next_free_vgpr 242
		.amdhsa_next_free_sgpr 98
		.amdhsa_accum_offset 244
		.amdhsa_reserve_vcc 1
		.amdhsa_float_round_mode_32 0
		.amdhsa_float_round_mode_16_64 0
		.amdhsa_float_denorm_mode_32 3
		.amdhsa_float_denorm_mode_16_64 3
		.amdhsa_dx10_clamp 1
		.amdhsa_ieee_mode 1
		.amdhsa_fp16_overflow 0
		.amdhsa_tg_split 0
		.amdhsa_exception_fp_ieee_invalid_op 0
		.amdhsa_exception_fp_denorm_src 0
		.amdhsa_exception_fp_ieee_div_zero 0
		.amdhsa_exception_fp_ieee_overflow 0
		.amdhsa_exception_fp_ieee_underflow 0
		.amdhsa_exception_fp_ieee_inexact 0
		.amdhsa_exception_int_div_zero 0
	.end_amdhsa_kernel

amdhsa.kernels:
  - .agpr_count:     0
    .args:
      - .offset:         0
        .size:           120
        .value_kind:     by_value
      - .offset:         120
        .size:           4
        .value_kind:     hidden_block_count_x
      - .offset:         124
        .size:           4
        .value_kind:     hidden_block_count_y
      - .offset:         128
        .size:           4
        .value_kind:     hidden_block_count_z
      - .offset:         132
        .size:           2
        .value_kind:     hidden_group_size_x
      - .offset:         134
        .size:           2
        .value_kind:     hidden_group_size_y
      - .offset:         136
        .size:           2
        .value_kind:     hidden_group_size_z
      - .offset:         138
        .size:           2
        .value_kind:     hidden_remainder_x
      - .offset:         140
        .size:           2
        .value_kind:     hidden_remainder_y
      - .offset:         142
        .size:           2
        .value_kind:     hidden_remainder_z
      - .offset:         160
        .size:           8
        .value_kind:     hidden_global_offset_x
      - .offset:         168
        .size:           8
        .value_kind:     hidden_global_offset_y
      - .offset:         176
        .size:           8
        .value_kind:     hidden_global_offset_z
      - .offset:         184
        .size:           2
        .value_kind:     hidden_grid_dims
      - .offset:         208
        .size:           8
        .value_kind:     hidden_multigrid_sync_arg
      - .offset:         240
        .size:           4
        .value_kind:     hidden_dynamic_lds_size
    .group_segment_fixed_size: 0
    .kernarg_segment_align: 8
    .kernarg_segment_size: 376
    .language:       OpenCL C
    .language_version:
      - 2
      - 0
    .max_flat_workgroup_size: 512
    .name:           _Z8yoco_fwd4Args
    .private_segment_fixed_size: 0
    .sgpr_count:     104
    .sgpr_spill_count: 3
    .symbol:         _Z8yoco_fwd4Args.kd
    .uniform_work_group_size: 1
    .uses_dynamic_stack: false
    .vgpr_count:     242
    .vgpr_spill_count: 0
    .wavefront_size: 64
